# SWA inner loop: twelve of the sixteen V-tile LDS reads of the PV product issued up front into free VGPRs, the last four behind the first MFMA pair, counted lgkmcnt waits
# baseline (speedup 1.0000x reference)
.LBB0_583:
	s_add_i32 s12, s77, s78
	s_setprio 1
	v_add_u32_e32 v0, s12, v125
	v_add_u32_e32 v99, s12, v126
	ds_read_b64_tr_b16 v[50:51], v0 offset:16384
	ds_read_b64_tr_b16 v[52:53], v0 offset:17408
	ds_read_b64_tr_b16 v[54:55], v0 offset:18432
	ds_read_b64_tr_b16 v[56:57], v0 offset:19456
	ds_read_b64_tr_b16 v[132:133], v0 offset:20480
	ds_read_b64_tr_b16 v[134:135], v0 offset:21504
	ds_read_b64_tr_b16 v[136:137], v0 offset:22528
	ds_read_b64_tr_b16 v[138:139], v0 offset:23552
	ds_read_b64_tr_b16 v[148:149], v99 offset:16384
	ds_read_b64_tr_b16 v[150:151], v99 offset:17408
	ds_read_b64_tr_b16 v[152:153], v99 offset:18432
	ds_read_b64_tr_b16 v[154:155], v99 offset:19456
	s_waitcnt lgkmcnt(10)
	v_mfma_f32_32x32x16_bf16 v[2:17], v[50:53], v[34:37], v[2:17]
	s_waitcnt lgkmcnt(8)
	v_mfma_f32_32x32x16_bf16 v[2:17], v[54:57], v[42:45], v[2:17]
	ds_read_b64_tr_b16 v[156:157], v99 offset:20480
	ds_read_b64_tr_b16 v[158:159], v99 offset:21504
	ds_read_b64_tr_b16 v[160:161], v99 offset:22528
	ds_read_b64_tr_b16 v[162:163], v99 offset:23552
	s_waitcnt lgkmcnt(10)
	v_mfma_f32_32x32x16_bf16 v[2:17], v[132:135], v[38:41], v[2:17]
	s_waitcnt lgkmcnt(8)
	v_mfma_f32_32x32x16_bf16 v[2:17], v[136:139], v[46:49], v[2:17]
	s_waitcnt lgkmcnt(6)
	v_mfma_f32_32x32x16_bf16 v[18:33], v[148:151], v[34:37], v[18:33]
	s_waitcnt lgkmcnt(4)
	v_mfma_f32_32x32x16_bf16 v[18:33], v[152:155], v[42:45], v[18:33]
	s_waitcnt lgkmcnt(2)
	v_mfma_f32_32x32x16_bf16 v[18:33], v[156:159], v[38:41], v[18:33]
	s_waitcnt lgkmcnt(0)
	v_mfma_f32_32x32x16_bf16 v[18:33], v[160:163], v[46:49], v[18:33]
	s_setprio 0
	s_branch .LBB0_575
